# GEMM K-loop: end-of-MMA s_barrier moved up by 2 MFMAs (trailing MFMAs issue after the barrier)
# baseline (speedup 1.0000x reference)
; #define PG8_STAGE(bufoff, gbase, voff) do { _Pragma("unroll") for (int _i = 0; _i < 2; ++_i) \
;     __builtin_amdgcn_global_load_lds((const unsigned*)((const char*)(gbase) + (voff)[_i]), (LAS unsigned*)(lds + (bufoff) + ldsw + _i * 8192), 16, 0, 0); } while (0)
; #define PG8_LDA(dst, b, h) do { _Pragma("unroll") for (int m = 0; m < 4; ++m) _Pragma("unroll") for (int k = 0; k < 2; ++k) dst[m][k] = *(const LAS bf16x8*)(lds + PG8_SA(b, h) + aoff + m * 2048 + k * 1024); } while (0)
; #define PG8_LDB(dst, b, h) do { _Pragma("unroll") for (int n = 0; n < 2; ++n) _Pragma("unroll") for (int k = 0; k < 2; ++k) dst[n][k] = *(const LAS bf16x8*)(lds + PG8_SB(b, h) + boff + n * 2048 + k * 1024); } while (0)
; #define PG8_MMA(ai, bj, At, Bt) do { __builtin_amdgcn_s_setprio(1); _Pragma("unroll") for (int m = 0; m < 4; ++m) _Pragma("unroll") for (int n = 0; n < 2; ++n) _Pragma("unroll") for (int k = 0; k < 2; ++k) \
;     acc[ai][bj][m][n] = __builtin_amdgcn_mfma_f32_16x16x32_bf16(Bt[n][k], At[m][k], acc[ai][bj][m][n], 0, 0, 0); __builtin_amdgcn_s_setprio(0); } while (0)
; #define PG8_WAIT_V(n) asm volatile("s_waitcnt vmcnt(" #n ")" ::: "memory")
; #define PG8_WAIT_L(n) asm volatile("s_waitcnt lgkmcnt(" #n ")" ::: "memory")
; #define PG8_BAR __builtin_amdgcn_s_barrier()
; #define PG8_SCHED __builtin_amdgcn_sched_barrier(0)
; template <class Epi>
; __device__ __forceinline__ void gemm_phase(LAS unsigned char* lds, const Gemm g, const StaticOrder& S, const Epi& E) {
;     ...
;       PG8_LDB(B0, 0, 0); PG8_SCHED; PG8_LDA(At, 0, 0); PG8_STAGE(PG8_SA(1, 1), a1 + hstep, voffA);
;       PG8_WAIT_L(8); PG8_BAR; PG8_WAIT_L(0); PG8_MMA(0, 0, At, B0); PG8_BAR; PG8_SCHED;
;       PG8_LDB(B1, 0, 1); PG8_STAGE(PG8_SB(0, 0), b2, voffB);
;       PG8_BAR; PG8_WAIT_L(0); PG8_MMA(0, 1, At, B1); PG8_BAR;
;       PG8_LDA(At, 0, 1); PG8_STAGE(PG8_SA(0, 0), a2, voffA);
;       PG8_BAR; PG8_WAIT_L(0); PG8_MMA(1, 0, At, B0); PG8_BAR; PG8_SCHED;
;       PG8_STAGE(PG8_SB(0, 1), b2 + hstep, voffB);
;       PG8_WAIT_V(6); PG8_BAR; PG8_MMA(1, 1, At, B1); PG8_BAR;
.LBB0_56:
	s_add_i32 s76, s10, 2
	s_add_u32 s12, s0, 0x80
	s_addc_u32 s11, s1, 0
	s_add_i32 s77, 0, 0x10000
	s_waitcnt lgkmcnt(0)
	v_add_u32_e32 v80, s77, v187
	ds_read_b128 v[130:133], v80
	ds_read_b128 v[134:137], v80 offset:1024
	ds_read_b128 v[138:141], v80 offset:2048
	ds_read_b128 v[142:145], v80 offset:3072
	s_cmp_eq_u32 s21, s10
	s_cselect_b32 s10, s18, s12
	s_cselect_b32 s11, s19, s11
	s_cselect_b32 s13, s17, s75
	s_cselect_b32 s12, s16, s74
	v_lshl_add_u64 v[194:195], s[0:1], 0, v[172:173]
	s_add_i32 m0, s15, 0xc000
	ds_read_b128 v[146:149], v189
	ds_read_b128 v[150:153], v189 offset:1024
	ds_read_b128 v[154:157], v189 offset:2048
	ds_read_b128 v[158:161], v189 offset:3072
	ds_read_b128 v[174:177], v189 offset:4096
	ds_read_b128 v[178:181], v189 offset:5120
	ds_read_b128 v[182:185], v189 offset:6144
	ds_read_b128 v[190:193], v189 offset:7168
	global_load_lds_dwordx4 v[194:195], off
	v_lshl_add_u64 v[194:195], s[0:1], 0, v[170:171]
	s_add_i32 m0, s15, 0xe000
	s_nop 0
	global_load_lds_dwordx4 v[194:195], off
	s_waitcnt lgkmcnt(8)
	s_barrier
	s_waitcnt lgkmcnt(0)
	s_waitcnt lgkmcnt(0)
	v_mfma_f32_16x16x32_bf16 v[126:129], v[130:133], v[146:149], v[126:129]
	v_mfma_f32_16x16x32_bf16 v[122:125], v[138:141], v[146:149], v[122:125]
	v_mfma_f32_16x16x32_bf16 v[118:121], v[130:133], v[154:157], v[118:121]
	v_mfma_f32_16x16x32_bf16 v[114:117], v[138:141], v[154:157], v[114:117]
	v_mfma_f32_16x16x32_bf16 v[110:113], v[130:133], v[174:177], v[110:113]
	v_mfma_f32_16x16x32_bf16 v[106:109], v[138:141], v[174:177], v[106:109]
	v_mfma_f32_16x16x32_bf16 v[102:105], v[130:133], v[182:185], v[102:105]
	v_mfma_f32_16x16x32_bf16 v[98:101], v[138:141], v[182:185], v[98:101]
	v_mfma_f32_16x16x32_bf16 v[126:129], v[134:137], v[150:153], v[126:129]
	v_mfma_f32_16x16x32_bf16 v[122:125], v[142:145], v[150:153], v[122:125]
	v_mfma_f32_16x16x32_bf16 v[118:121], v[134:137], v[158:161], v[118:121]
	v_mfma_f32_16x16x32_bf16 v[114:117], v[142:145], v[158:161], v[114:117]
	v_mfma_f32_16x16x32_bf16 v[110:113], v[134:137], v[178:181], v[110:113]
	v_mfma_f32_16x16x32_bf16 v[106:109], v[142:145], v[178:181], v[106:109]
	s_barrier
	v_mfma_f32_16x16x32_bf16 v[102:105], v[134:137], v[190:193], v[102:105]
	v_mfma_f32_16x16x32_bf16 v[98:101], v[142:145], v[190:193], v[98:101]
	s_add_i32 s78, 0, 0x14000
	s_add_i32 s77, s77, s14
	v_add_u32_e32 v80, s78, v187
	v_lshl_add_u64 v[210:211], s[12:13], 0, v[164:165]
	s_mov_b32 m0, s77
	ds_read_b128 v[194:197], v80
	ds_read_b128 v[198:201], v80 offset:1024
	ds_read_b128 v[202:205], v80 offset:2048
	ds_read_b128 v[206:209], v80 offset:3072
	global_load_lds_dwordx4 v[210:211], off
	v_lshl_add_u64 v[212:213], s[12:13], 0, v[168:169]
	s_add_i32 m0, s77, 0x2000
	s_nop 0
	global_load_lds_dwordx4 v[212:213], off
	s_barrier
	s_waitcnt lgkmcnt(0)
	s_waitcnt lgkmcnt(0)
	v_mfma_f32_16x16x32_bf16 v[60:63], v[194:197], v[146:149], v[60:63]
	v_mfma_f32_16x16x32_bf16 v[56:59], v[202:205], v[146:149], v[56:59]
	v_mfma_f32_16x16x32_bf16 v[52:55], v[194:197], v[154:157], v[52:55]
	v_mfma_f32_16x16x32_bf16 v[48:51], v[202:205], v[154:157], v[48:51]
	v_mfma_f32_16x16x32_bf16 v[44:47], v[194:197], v[174:177], v[44:47]
	v_mfma_f32_16x16x32_bf16 v[40:43], v[202:205], v[174:177], v[40:43]
	v_mfma_f32_16x16x32_bf16 v[36:39], v[194:197], v[182:185], v[36:39]
	v_mfma_f32_16x16x32_bf16 v[32:35], v[202:205], v[182:185], v[32:35]
	v_mfma_f32_16x16x32_bf16 v[60:63], v[198:201], v[150:153], v[60:63]
	v_mfma_f32_16x16x32_bf16 v[56:59], v[206:209], v[150:153], v[56:59]
	v_mfma_f32_16x16x32_bf16 v[52:55], v[198:201], v[158:161], v[52:55]
	v_mfma_f32_16x16x32_bf16 v[48:51], v[206:209], v[158:161], v[48:51]
	v_mfma_f32_16x16x32_bf16 v[44:47], v[198:201], v[178:181], v[44:47]
	v_mfma_f32_16x16x32_bf16 v[40:43], v[206:209], v[178:181], v[40:43]
	s_barrier
	v_mfma_f32_16x16x32_bf16 v[36:39], v[198:201], v[190:193], v[36:39]
	v_mfma_f32_16x16x32_bf16 v[32:35], v[206:209], v[190:193], v[32:35]
	s_mov_b32 m0, s15
	v_lshl_add_u64 v[216:217], s[10:11], 0, v[162:163]
	ds_read_b128 v[146:149], v189 offset:16384
	ds_read_b128 v[150:153], v189 offset:17408
	ds_read_b128 v[154:157], v189 offset:18432
	ds_read_b128 v[158:161], v189 offset:19456
	ds_read_b128 v[174:177], v189 offset:20480
	ds_read_b128 v[178:181], v189 offset:21504
	ds_read_b128 v[182:185], v189 offset:22528
	ds_read_b128 v[190:193], v189 offset:23552
	global_load_lds_dwordx4 v[216:217], off
	v_lshl_add_u64 v[232:233], s[10:11], 0, v[166:167]
	s_mov_b32 m0, s84
	s_nop 0
	global_load_lds_dwordx4 v[232:233], off
	s_barrier
	s_waitcnt lgkmcnt(0)
	s_waitcnt lgkmcnt(0)
	v_mfma_f32_16x16x32_bf16 v[94:97], v[130:133], v[146:149], v[94:97]
	v_mfma_f32_16x16x32_bf16 v[90:93], v[138:141], v[146:149], v[90:93]
	v_mfma_f32_16x16x32_bf16 v[86:89], v[130:133], v[154:157], v[86:89]
	v_mfma_f32_16x16x32_bf16 v[82:85], v[138:141], v[154:157], v[82:85]
	v_mfma_f32_16x16x32_bf16 v[76:79], v[130:133], v[174:177], v[76:79]
	v_mfma_f32_16x16x32_bf16 v[72:75], v[138:141], v[174:177], v[72:75]
	v_mfma_f32_16x16x32_bf16 v[68:71], v[130:133], v[182:185], v[68:71]
	v_mfma_f32_16x16x32_bf16 v[64:67], v[138:141], v[182:185], v[64:67]
	v_mfma_f32_16x16x32_bf16 v[94:97], v[134:137], v[150:153], v[94:97]
	v_mfma_f32_16x16x32_bf16 v[90:93], v[142:145], v[150:153], v[90:93]
	v_mfma_f32_16x16x32_bf16 v[86:89], v[134:137], v[158:161], v[86:89]
	v_mfma_f32_16x16x32_bf16 v[82:85], v[142:145], v[158:161], v[82:85]
	v_mfma_f32_16x16x32_bf16 v[76:79], v[134:137], v[178:181], v[76:79]
	v_mfma_f32_16x16x32_bf16 v[72:75], v[142:145], v[178:181], v[72:75]
	s_barrier
; #define PG8_STAGE(bufoff, gbase, voff) do { _Pragma("unroll") for (int _i = 0; _i < 2; ++_i) \
;     __builtin_amdgcn_global_load_lds((const unsigned*)((const char*)(gbase) + (voff)[_i]), (LAS unsigned*)(lds + (bufoff) + ldsw + _i * 8192), 16, 0, 0); } while (0)
; #define PG8_LDA(dst, b, h) do { _Pragma("unroll") for (int m = 0; m < 4; ++m) _Pragma("unroll") for (int k = 0; k < 2; ++k) dst[m][k] = *(const LAS bf16x8*)(lds + PG8_SA(b, h) + aoff + m * 2048 + k * 1024); } while (0)
; #define PG8_LDB(dst, b, h) do { _Pragma("unroll") for (int n = 0; n < 2; ++n) _Pragma("unroll") for (int k = 0; k < 2; ++k) dst[n][k] = *(const LAS bf16x8*)(lds + PG8_SB(b, h) + boff + n * 2048 + k * 1024); } while (0)
; #define PG8_MMA(ai, bj, At, Bt) do { __builtin_amdgcn_s_setprio(1); _Pragma("unroll") for (int m = 0; m < 4; ++m) _Pragma("unroll") for (int n = 0; n < 2; ++n) _Pragma("unroll") for (int k = 0; k < 2; ++k) \
;     acc[ai][bj][m][n] = __builtin_amdgcn_mfma_f32_16x16x32_bf16(Bt[n][k], At[m][k], acc[ai][bj][m][n], 0, 0, 0); __builtin_amdgcn_s_setprio(0); } while (0)
; #define PG8_WAIT_V(n) asm volatile("s_waitcnt vmcnt(" #n ")" ::: "memory")
; #define PG8_WAIT_L(n) asm volatile("s_waitcnt lgkmcnt(" #n ")" ::: "memory")
; #define PG8_BAR __builtin_amdgcn_s_barrier()
; #define PG8_SCHED __builtin_amdgcn_sched_barrier(0)
; template <class Epi>
; __device__ __forceinline__ void gemm_phase(LAS unsigned char* lds, const Gemm g, const StaticOrder& S, const Epi& E) {
;     ...
;       PG8_WAIT_V(6); PG8_BAR; PG8_MMA(1, 1, At, B1); PG8_BAR;
;       PG8_LDB(B0, 1, 0); PG8_SCHED; PG8_LDA(At, 1, 0); PG8_STAGE(PG8_SA(0, 1), a2 + hstep, voffA);
;       PG8_WAIT_L(8); PG8_BAR; PG8_WAIT_L(0); PG8_MMA(0, 0, At, B0); PG8_BAR; PG8_SCHED;
;       PG8_LDB(B1, 1, 1); PG8_STAGE(PG8_SB(1, 0), b3, voffB);
;       PG8_BAR; PG8_WAIT_L(0); PG8_MMA(0, 1, At, B1); PG8_BAR;
;       PG8_LDA(At, 1, 1); PG8_STAGE(PG8_SA(1, 0), a3, voffA);
;       PG8_BAR; PG8_WAIT_L(0); PG8_MMA(1, 0, At, B0); PG8_BAR; PG8_SCHED;
	v_mfma_f32_16x16x32_bf16 v[68:71], v[134:137], v[190:193], v[68:71]
	v_mfma_f32_16x16x32_bf16 v[64:67], v[142:145], v[190:193], v[64:67]
	s_add_u32 s12, s12, s64
	s_addc_u32 s13, s13, 0
	s_add_i32 s77, s78, s14
	v_lshl_add_u64 v[236:237], s[12:13], 0, v[164:165]
	s_mov_b32 m0, s77
	v_lshl_add_u64 v[242:243], s[12:13], 0, v[168:169]
	global_load_lds_dwordx4 v[236:237], off
	s_add_i32 m0, s77, 0x2000
	s_nop 0
	global_load_lds_dwordx4 v[242:243], off
	s_waitcnt vmcnt(6)
	s_barrier
	v_mfma_f32_16x16x32_bf16 v[28:31], v[194:197], v[146:149], v[28:31]
	v_mfma_f32_16x16x32_bf16 v[24:27], v[202:205], v[146:149], v[24:27]
	v_mfma_f32_16x16x32_bf16 v[20:23], v[194:197], v[154:157], v[20:23]
	v_mfma_f32_16x16x32_bf16 v[16:19], v[202:205], v[154:157], v[16:19]
	v_mfma_f32_16x16x32_bf16 v[12:15], v[194:197], v[174:177], v[12:15]
	v_mfma_f32_16x16x32_bf16 v[8:11], v[202:205], v[174:177], v[8:11]
	v_mfma_f32_16x16x32_bf16 v[4:7], v[194:197], v[182:185], v[4:7]
	v_mfma_f32_16x16x32_bf16 v[0:3], v[202:205], v[182:185], v[0:3]
	v_mfma_f32_16x16x32_bf16 v[28:31], v[198:201], v[150:153], v[28:31]
	v_mfma_f32_16x16x32_bf16 v[24:27], v[206:209], v[150:153], v[24:27]
	v_mfma_f32_16x16x32_bf16 v[20:23], v[198:201], v[158:161], v[20:23]
	v_mfma_f32_16x16x32_bf16 v[16:19], v[206:209], v[158:161], v[16:19]
	v_mfma_f32_16x16x32_bf16 v[12:15], v[198:201], v[178:181], v[12:15]
	v_mfma_f32_16x16x32_bf16 v[8:11], v[206:209], v[178:181], v[8:11]
	s_barrier
	v_mfma_f32_16x16x32_bf16 v[4:7], v[198:201], v[190:193], v[4:7]
	v_mfma_f32_16x16x32_bf16 v[0:3], v[206:209], v[190:193], v[0:3]
	s_add_i32 s12, 0, 0x18000
	v_add_u32_e32 v80, s12, v187
	ds_read_b128 v[130:133], v80
	ds_read_b128 v[134:137], v80 offset:1024
	ds_read_b128 v[138:141], v80 offset:2048
	ds_read_b128 v[142:145], v80 offset:3072
	s_add_u32 s10, s10, s64
	s_addc_u32 s11, s11, 0
	s_mov_b32 m0, s99
	v_lshl_add_u64 v[194:195], s[10:11], 0, v[162:163]
	ds_read_b128 v[146:149], v189 offset:32768
	ds_read_b128 v[150:153], v189 offset:33792
	ds_read_b128 v[154:157], v189 offset:34816
	ds_read_b128 v[158:161], v189 offset:35840
	ds_read_b128 v[174:177], v189 offset:36864
	ds_read_b128 v[178:181], v189 offset:37888
	ds_read_b128 v[182:185], v189 offset:38912
	ds_read_b128 v[190:193], v189 offset:39936
	global_load_lds_dwordx4 v[194:195], off
	v_lshl_add_u64 v[194:195], s[10:11], 0, v[166:167]
	s_mov_b32 m0, s33
	s_nop 0
	global_load_lds_dwordx4 v[194:195], off
	s_waitcnt lgkmcnt(8)
	s_barrier
	s_waitcnt lgkmcnt(0)
	s_waitcnt lgkmcnt(0)
	v_mfma_f32_16x16x32_bf16 v[126:129], v[130:133], v[146:149], v[126:129]
	v_mfma_f32_16x16x32_bf16 v[122:125], v[138:141], v[146:149], v[122:125]
	v_mfma_f32_16x16x32_bf16 v[118:121], v[130:133], v[154:157], v[118:121]
	v_mfma_f32_16x16x32_bf16 v[114:117], v[138:141], v[154:157], v[114:117]
	v_mfma_f32_16x16x32_bf16 v[110:113], v[130:133], v[174:177], v[110:113]
	v_mfma_f32_16x16x32_bf16 v[106:109], v[138:141], v[174:177], v[106:109]
	v_mfma_f32_16x16x32_bf16 v[102:105], v[130:133], v[182:185], v[102:105]
	v_mfma_f32_16x16x32_bf16 v[98:101], v[138:141], v[182:185], v[98:101]
	v_mfma_f32_16x16x32_bf16 v[126:129], v[134:137], v[150:153], v[126:129]
	v_mfma_f32_16x16x32_bf16 v[122:125], v[142:145], v[150:153], v[122:125]
	v_mfma_f32_16x16x32_bf16 v[118:121], v[134:137], v[158:161], v[118:121]
	v_mfma_f32_16x16x32_bf16 v[114:117], v[142:145], v[158:161], v[114:117]
	v_mfma_f32_16x16x32_bf16 v[110:113], v[134:137], v[178:181], v[110:113]
	v_mfma_f32_16x16x32_bf16 v[106:109], v[142:145], v[178:181], v[106:109]
	s_barrier
	v_mfma_f32_16x16x32_bf16 v[102:105], v[134:137], v[190:193], v[102:105]
	v_mfma_f32_16x16x32_bf16 v[98:101], v[142:145], v[190:193], v[98:101]
	s_add_i32 s10, 0, 0x1c000
	s_add_i32 s11, s12, s14
	v_add_u32_e32 v80, s10, v187
	v_lshl_add_u64 v[210:211], v[210:211], 0, s[90:91]
	s_mov_b32 m0, s11
	ds_read_b128 v[194:197], v80
	ds_read_b128 v[198:201], v80 offset:1024
	ds_read_b128 v[202:205], v80 offset:2048
	ds_read_b128 v[206:209], v80 offset:3072
	global_load_lds_dwordx4 v[210:211], off
	v_lshl_add_u64 v[210:211], v[212:213], 0, s[90:91]
	s_add_i32 m0, s11, 0x2000
	s_nop 0
	global_load_lds_dwordx4 v[210:211], off
	s_barrier
	s_waitcnt lgkmcnt(0)
	s_waitcnt lgkmcnt(0)
	v_mfma_f32_16x16x32_bf16 v[60:63], v[194:197], v[146:149], v[60:63]
	v_mfma_f32_16x16x32_bf16 v[56:59], v[202:205], v[146:149], v[56:59]
	v_mfma_f32_16x16x32_bf16 v[52:55], v[194:197], v[154:157], v[52:55]
	v_mfma_f32_16x16x32_bf16 v[48:51], v[202:205], v[154:157], v[48:51]
	v_mfma_f32_16x16x32_bf16 v[44:47], v[194:197], v[174:177], v[44:47]
	v_mfma_f32_16x16x32_bf16 v[40:43], v[202:205], v[174:177], v[40:43]
	v_mfma_f32_16x16x32_bf16 v[36:39], v[194:197], v[182:185], v[36:39]
	v_mfma_f32_16x16x32_bf16 v[32:35], v[202:205], v[182:185], v[32:35]
	v_mfma_f32_16x16x32_bf16 v[60:63], v[198:201], v[150:153], v[60:63]
	v_mfma_f32_16x16x32_bf16 v[56:59], v[206:209], v[150:153], v[56:59]
	v_mfma_f32_16x16x32_bf16 v[52:55], v[198:201], v[158:161], v[52:55]
	v_mfma_f32_16x16x32_bf16 v[48:51], v[206:209], v[158:161], v[48:51]
	v_mfma_f32_16x16x32_bf16 v[44:47], v[198:201], v[178:181], v[44:47]
	v_mfma_f32_16x16x32_bf16 v[40:43], v[206:209], v[178:181], v[40:43]
	s_barrier
	v_mfma_f32_16x16x32_bf16 v[36:39], v[198:201], v[190:193], v[36:39]
	v_mfma_f32_16x16x32_bf16 v[32:35], v[206:209], v[190:193], v[32:35]
	s_mov_b32 m0, s29
	v_lshl_add_u64 v[210:211], v[216:217], 0, s[90:91]
	ds_read_b128 v[146:149], v189 offset:49152
	ds_read_b128 v[150:153], v189 offset:50176
	ds_read_b128 v[154:157], v189 offset:51200
	ds_read_b128 v[158:161], v189 offset:52224
	ds_read_b128 v[174:177], v189 offset:53248
	ds_read_b128 v[178:181], v189 offset:54272
	ds_read_b128 v[182:185], v189 offset:55296
	ds_read_b128 v[190:193], v189 offset:56320
	global_load_lds_dwordx4 v[210:211], off
	v_lshl_add_u64 v[210:211], v[232:233], 0, s[90:91]
	s_mov_b32 m0, s20
	s_nop 0
	global_load_lds_dwordx4 v[210:211], off
	s_barrier
; #define PG8_STAGE(bufoff, gbase, voff) do { _Pragma("unroll") for (int _i = 0; _i < 2; ++_i) \
;     __builtin_amdgcn_global_load_lds((const unsigned*)((const char*)(gbase) + (voff)[_i]), (LAS unsigned*)(lds + (bufoff) + ldsw + _i * 8192), 16, 0, 0); } while (0)
; #define PG8_MMA(ai, bj, At, Bt) do { __builtin_amdgcn_s_setprio(1); _Pragma("unroll") for (int m = 0; m < 4; ++m) _Pragma("unroll") for (int n = 0; n < 2; ++n) _Pragma("unroll") for (int k = 0; k < 2; ++k) \
;     acc[ai][bj][m][n] = __builtin_amdgcn_mfma_f32_16x16x32_bf16(Bt[n][k], At[m][k], acc[ai][bj][m][n], 0, 0, 0); __builtin_amdgcn_s_setprio(0); } while (0)
; #define PG8_WAIT_V(n) asm volatile("s_waitcnt vmcnt(" #n ")" ::: "memory")
; #define PG8_WAIT_L(n) asm volatile("s_waitcnt lgkmcnt(" #n ")" ::: "memory")
; #define PG8_BAR __builtin_amdgcn_s_barrier()
; #define PG8_SCHED __builtin_amdgcn_sched_barrier(0)
; template <class Epi>
; __device__ __forceinline__ void gemm_phase(LAS unsigned char* lds, const Gemm g, const StaticOrder& S, const Epi& E) {
;     ...
;       PG8_BAR; PG8_WAIT_L(0); PG8_MMA(1, 0, At, B0); PG8_BAR; PG8_SCHED;
;       PG8_STAGE(PG8_SB(1, 1), b3 + hstep, voffB);
;       PG8_WAIT_V(6); PG8_BAR; PG8_MMA(1, 1, At, B1); PG8_BAR;
;     }
;     E(acc, cur, wr, wc, fr, fq);
;     if (!has_next) break;
;   __device__ __forceinline__ void operator()(const f32x4 (&acc)[2][2][4][2], const pg8::Unit& u, int wr, int wc, int fr, int fq) const {
;     ...
;       float* xo = P->out + (size_t)slice * TS * DM; const u16* x2b = (const u16*)(ws + O_X2B) + (size_t)slice * TS * DM;
; #pragma unroll
;       for (int ai = 0; ai < 2; ++ai) {
;         u32x4 xv[4][2];
; #pragma unroll
;         for (int m = 0; m < 4; ++m)
; #pragma unroll
;           for (int bj = 0; bj < 2; ++bj) xv[m][bj] = *(const u32x4*)(x2b + (size_t)(row0 + ai * 128 + m * 16) * DM + col0 + bj * 128);
	s_waitcnt lgkmcnt(0)
	s_waitcnt lgkmcnt(0)
	v_mfma_f32_16x16x32_bf16 v[94:97], v[130:133], v[146:149], v[94:97]
	v_mfma_f32_16x16x32_bf16 v[90:93], v[138:141], v[146:149], v[90:93]
	v_mfma_f32_16x16x32_bf16 v[86:89], v[130:133], v[154:157], v[86:89]
	v_mfma_f32_16x16x32_bf16 v[82:85], v[138:141], v[154:157], v[82:85]
	v_mfma_f32_16x16x32_bf16 v[76:79], v[130:133], v[174:177], v[76:79]
	v_mfma_f32_16x16x32_bf16 v[72:75], v[138:141], v[174:177], v[72:75]
	v_mfma_f32_16x16x32_bf16 v[68:71], v[130:133], v[182:185], v[68:71]
	v_mfma_f32_16x16x32_bf16 v[64:67], v[138:141], v[182:185], v[64:67]
	v_mfma_f32_16x16x32_bf16 v[94:97], v[134:137], v[150:153], v[94:97]
	v_mfma_f32_16x16x32_bf16 v[90:93], v[142:145], v[150:153], v[90:93]
	v_mfma_f32_16x16x32_bf16 v[86:89], v[134:137], v[158:161], v[86:89]
	v_mfma_f32_16x16x32_bf16 v[82:85], v[142:145], v[158:161], v[82:85]
	v_mfma_f32_16x16x32_bf16 v[76:79], v[134:137], v[178:181], v[76:79]
	v_mfma_f32_16x16x32_bf16 v[72:75], v[142:145], v[178:181], v[72:75]
	s_barrier
	v_mfma_f32_16x16x32_bf16 v[68:71], v[134:137], v[190:193], v[68:71]
	v_mfma_f32_16x16x32_bf16 v[64:67], v[142:145], v[190:193], v[64:67]
	s_add_i32 s10, s10, s14
	v_lshl_add_u64 v[130:131], v[236:237], 0, s[90:91]
	s_mov_b32 m0, s10
	s_nop 0
	global_load_lds_dwordx4 v[130:131], off
	v_lshl_add_u64 v[130:131], v[242:243], 0, s[90:91]
	s_add_i32 m0, s10, 0x2000
	s_nop 0
	global_load_lds_dwordx4 v[130:131], off
	s_waitcnt vmcnt(6)
	s_barrier
	v_mfma_f32_16x16x32_bf16 v[28:31], v[194:197], v[146:149], v[28:31]
	v_mfma_f32_16x16x32_bf16 v[24:27], v[202:205], v[146:149], v[24:27]
	v_mfma_f32_16x16x32_bf16 v[20:23], v[194:197], v[154:157], v[20:23]
	v_mfma_f32_16x16x32_bf16 v[16:19], v[202:205], v[154:157], v[16:19]
	v_mfma_f32_16x16x32_bf16 v[12:15], v[194:197], v[174:177], v[12:15]
	v_mfma_f32_16x16x32_bf16 v[8:11], v[202:205], v[174:177], v[8:11]
	v_mfma_f32_16x16x32_bf16 v[4:7], v[194:197], v[182:185], v[4:7]
	v_mfma_f32_16x16x32_bf16 v[0:3], v[202:205], v[182:185], v[0:3]
	v_mfma_f32_16x16x32_bf16 v[28:31], v[198:201], v[150:153], v[28:31]
	v_mfma_f32_16x16x32_bf16 v[24:27], v[206:209], v[150:153], v[24:27]
	v_mfma_f32_16x16x32_bf16 v[20:23], v[198:201], v[158:161], v[20:23]
	v_mfma_f32_16x16x32_bf16 v[16:19], v[206:209], v[158:161], v[16:19]
	v_mfma_f32_16x16x32_bf16 v[12:15], v[198:201], v[178:181], v[12:15]
	v_mfma_f32_16x16x32_bf16 v[8:11], v[206:209], v[178:181], v[8:11]
	s_barrier
	v_mfma_f32_16x16x32_bf16 v[4:7], v[198:201], v[190:193], v[4:7]
	v_mfma_f32_16x16x32_bf16 v[0:3], v[206:209], v[190:193], v[0:3]
	s_add_u32 s74, s74, 0x100
	s_addc_u32 s75, s75, 0
	s_add_u32 s0, s0, 0x100
	s_addc_u32 s1, s1, 0
	s_cmp_ge_u32 s76, s2
	s_mov_b32 s10, s76
	s_cbranch_scc0 .LBB0_56
	s_cmp_lg_u32 s71, 0
	s_cselect_b64 s[0:1], -1, 0
	s_cmp_eq_u32 s71, 0
	s_cselect_b32 s10, s73, s72
	s_cselect_b32 s11, s72, s73
	s_lshl_b32 s71, s10, 8
	s_add_i32 s71, s71, s28
	v_or_b32_e32 v176, s71, v186
	v_lshl_or_b32 v174, s11, 8, v188
	s_cmp_lt_i32 s98, 2
	s_mov_b64 s[10:11], -1
	s_cbranch_scc1 .LBB0_151
	s_cmp_lt_i32 s98, 4
	s_cbranch_scc1 .LBB0_84
	s_cmp_lt_i32 s98, 5
	s_cbranch_scc1 .LBB0_65
	s_cmp_lg_u32 s98, 5
	s_cbranch_scc0 .LBB0_62
	v_readlane_b32 s10, v254, 18
	v_ashrrev_i32_e32 v175, 31, v174
	v_readlane_b32 s11, v254, 19
	v_ashrrev_i32_e32 v177, 31, v176
	v_lshlrev_b64 v[130:131], 11, v[176:177]
	v_lshl_add_u64 v[136:137], v[174:175], 1, s[10:11]
	v_or_b32_e32 v190, 16, v176
	v_lshl_add_u64 v[130:131], v[136:137], 0, v[130:131]
	v_ashrrev_i32_e32 v191, 31, v190
	flat_load_dwordx4 v[138:141], v[130:131]
	flat_load_dwordx4 v[142:145], v[130:131] offset:256
	v_lshlrev_b64 v[130:131], 11, v[190:191]
	v_or_b32_e32 v192, 32, v176
	v_lshl_add_u64 v[130:131], v[136:137], 0, v[130:131]
	v_ashrrev_i32_e32 v193, 31, v192
	flat_load_dwordx4 v[146:149], v[130:131]
	flat_load_dwordx4 v[150:153], v[130:131] offset:256
	v_lshlrev_b64 v[130:131], 11, v[192:193]
	v_or_b32_e32 v194, 48, v176
	v_lshl_add_u64 v[130:131], v[136:137], 0, v[130:131]
	v_ashrrev_i32_e32 v195, 31, v194
	flat_load_dwordx4 v[154:157], v[130:131]
	flat_load_dwordx4 v[158:161], v[130:131] offset:256
	v_lshlrev_b64 v[130:131], 11, v[194:195]
	v_lshl_add_u64 v[130:131], v[136:137], 0, v[130:131]
	flat_load_dwordx4 v[178:181], v[130:131]
	s_nop 0
	flat_load_dwordx4 v[130:133], v[130:131] offset:256
	v_readlane_b32 s10, v254, 20
	v_readlane_b32 s11, v254, 21
	s_nop 1
	v_lshl_add_u64 v[134:135], v[174:175], 2, s[10:11]
	v_lshlrev_b64 v[182:183], 12, v[176:177]
	v_lshl_add_u64 v[196:197], v[134:135], 0, v[182:183]
	s_waitcnt vmcnt(0) lgkmcnt(0)
; __device__ __forceinline__ float lo16(unsigned v) { return __uint_as_float(v << 16); }
; __device__ __forceinline__ float hi16(unsigned v) { return __uint_as_float(v & 0xffff0000u); }
;   __device__ __forceinline__ void operator()(const f32x4 (&acc)[2][2][4][2], const pg8::Unit& u, int wr, int wc, int fr, int fq) const {
;     ...
;           for (int bj = 0; bj < 2; ++bj) xv[m][bj] = *(const u32x4*)(x2b + (size_t)(row0 + ai * 128 + m * 16) * DM + col0 + bj * 128);
;         __builtin_amdgcn_sched_barrier(0);
; #pragma unroll
;         for (int m = 0; m < 4; ++m) {
;           const int row = row0 + ai * 128 + m * 16;
; #pragma unroll
;           for (int bj = 0; bj < 2; ++bj) {
;             float* d = xo + (size_t)row * DM + col0 + bj * 128;
;             const u32x4 x4 = xv[m][bj];
;             f32x4 o0 = acc[ai][bj][m][0], o1 = acc[ai][bj][m][1];
;             o0[0] += lo16(x4.x); o0[1] += hi16(x4.x); o0[2] += lo16(x4.y); o0[3] += hi16(x4.y); o1[0] += lo16(x4.z); o1[1] += hi16(x4.z); o1[2] += lo16(x4.w); o1[3] += hi16(x4.w);
;             *(f32x4*)d = o0; *(f32x4*)(d + 4) = o1;
;           }
;         }
	v_lshlrev_b32_e32 v182, 16, v138
	v_and_b32_e32 v183, 0xffff0000, v138
	v_lshlrev_b32_e32 v138, 16, v139
	v_and_b32_e32 v139, 0xffff0000, v139
	v_pk_add_f32 v[184:185], v[128:129], v[138:139]
	v_lshlrev_b32_e32 v138, 16, v140
	v_and_b32_e32 v139, 0xffff0000, v140
	v_lshlrev_b32_e32 v140, 16, v141
	v_and_b32_e32 v141, 0xffff0000, v141
	v_pk_add_f32 v[182:183], v[126:127], v[182:183]
	v_pk_add_f32 v[138:139], v[122:123], v[138:139]
	v_pk_add_f32 v[140:141], v[124:125], v[140:141]
	global_store_dwordx4 v[196:197], v[182:185], off
	global_store_dwordx4 v[196:197], v[138:141], off offset:16
	s_nop 1
	v_lshlrev_b32_e32 v138, 16, v142
	v_and_b32_e32 v139, 0xffff0000, v142
	v_lshlrev_b32_e32 v140, 16, v143
	v_and_b32_e32 v141, 0xffff0000, v143
	v_pk_add_f32 v[138:139], v[60:61], v[138:139]
	v_pk_add_f32 v[140:141], v[62:63], v[140:141]
	v_lshlrev_b32_e32 v142, 16, v144
	v_and_b32_e32 v143, 0xffff0000, v144
	v_lshlrev_b32_e32 v144, 16, v145
	v_and_b32_e32 v145, 0xffff0000, v145
	v_pk_add_f32 v[142:143], v[56:57], v[142:143]
	v_pk_add_f32 v[144:145], v[58:59], v[144:145]
	global_store_dwordx4 v[196:197], v[138:141], off offset:512
	global_store_dwordx4 v[196:197], v[142:145], off offset:528
	s_nop 0
	v_lshlrev_b64 v[138:139], 12, v[190:191]
	v_lshl_add_u64 v[182:183], v[134:135], 0, v[138:139]
	v_lshlrev_b32_e32 v138, 16, v146
	v_and_b32_e32 v139, 0xffff0000, v146
	v_lshlrev_b32_e32 v140, 16, v147
	v_and_b32_e32 v141, 0xffff0000, v147
	v_pk_add_f32 v[138:139], v[118:119], v[138:139]
	v_pk_add_f32 v[140:141], v[120:121], v[140:141]
	v_lshlrev_b32_e32 v142, 16, v148
	v_and_b32_e32 v143, 0xffff0000, v148
	v_lshlrev_b32_e32 v144, 16, v149
	v_and_b32_e32 v145, 0xffff0000, v149
	v_pk_add_f32 v[142:143], v[114:115], v[142:143]
	v_pk_add_f32 v[144:145], v[116:117], v[144:145]
	global_store_dwordx4 v[182:183], v[138:141], off
	global_store_dwordx4 v[182:183], v[142:145], off offset:16
	s_nop 0
	v_lshlrev_b32_e32 v138, 16, v150
	v_and_b32_e32 v139, 0xffff0000, v150
	v_lshlrev_b32_e32 v140, 16, v151
	v_and_b32_e32 v141, 0xffff0000, v151
	v_pk_add_f32 v[138:139], v[52:53], v[138:139]
	v_pk_add_f32 v[140:141], v[54:55], v[140:141]
	v_lshlrev_b32_e32 v142, 16, v152
	v_and_b32_e32 v143, 0xffff0000, v152
	v_lshlrev_b32_e32 v144, 16, v153
	v_and_b32_e32 v145, 0xffff0000, v153
	v_pk_add_f32 v[142:143], v[48:49], v[142:143]
	v_pk_add_f32 v[144:145], v[50:51], v[144:145]
	global_store_dwordx4 v[182:183], v[138:141], off offset:512
	global_store_dwordx4 v[182:183], v[142:145], off offset:528
	s_nop 0
	v_lshlrev_b64 v[138:139], 12, v[192:193]
	v_lshl_add_u64 v[146:147], v[134:135], 0, v[138:139]
	v_lshlrev_b32_e32 v138, 16, v154
	v_and_b32_e32 v139, 0xffff0000, v154
	v_lshlrev_b32_e32 v140, 16, v155
	v_and_b32_e32 v141, 0xffff0000, v155
	v_pk_add_f32 v[138:139], v[110:111], v[138:139]
	v_pk_add_f32 v[140:141], v[112:113], v[140:141]
	v_lshlrev_b32_e32 v142, 16, v156
	v_and_b32_e32 v143, 0xffff0000, v156
	v_lshlrev_b32_e32 v144, 16, v157
	v_and_b32_e32 v145, 0xffff0000, v157
	v_pk_add_f32 v[142:143], v[106:107], v[142:143]
	v_pk_add_f32 v[144:145], v[108:109], v[144:145]
	global_store_dwordx4 v[146:147], v[138:141], off
	global_store_dwordx4 v[146:147], v[142:145], off offset:16
	s_nop 0
	v_lshlrev_b32_e32 v138, 16, v158
	v_and_b32_e32 v139, 0xffff0000, v158
	v_lshlrev_b32_e32 v140, 16, v159
	v_and_b32_e32 v141, 0xffff0000, v159
	v_pk_add_f32 v[138:139], v[44:45], v[138:139]
	v_pk_add_f32 v[140:141], v[46:47], v[140:141]
	v_lshlrev_b32_e32 v142, 16, v160
	v_and_b32_e32 v143, 0xffff0000, v160
	v_lshlrev_b32_e32 v144, 16, v161
	v_and_b32_e32 v145, 0xffff0000, v161
	v_pk_add_f32 v[142:143], v[40:41], v[142:143]
	v_pk_add_f32 v[144:145], v[42:43], v[144:145]
	global_store_dwordx4 v[146:147], v[138:141], off offset:512
	global_store_dwordx4 v[146:147], v[142:145], off offset:528
	s_nop 0
	v_lshlrev_b64 v[138:139], 12, v[194:195]
	v_lshl_add_u64 v[146:147], v[134:135], 0, v[138:139]
	v_lshlrev_b32_e32 v138, 16, v178
	v_and_b32_e32 v139, 0xffff0000, v178
	v_lshlrev_b32_e32 v140, 16, v179
	v_and_b32_e32 v141, 0xffff0000, v179
	v_pk_add_f32 v[138:139], v[102:103], v[138:139]
	v_pk_add_f32 v[140:141], v[104:105], v[140:141]
	v_lshlrev_b32_e32 v142, 16, v180
	v_and_b32_e32 v143, 0xffff0000, v180
	v_lshlrev_b32_e32 v144, 16, v181
	v_and_b32_e32 v145, 0xffff0000, v181
	v_pk_add_f32 v[142:143], v[98:99], v[142:143]
	v_pk_add_f32 v[144:145], v[100:101], v[144:145]
	global_store_dwordx4 v[146:147], v[138:141], off
	global_store_dwordx4 v[146:147], v[142:145], off offset:16
	s_nop 0
	v_lshlrev_b32_e32 v138, 16, v130
	v_and_b32_e32 v139, 0xffff0000, v130
	v_lshlrev_b32_e32 v130, 16, v131
	v_and_b32_e32 v131, 0xffff0000, v131
	v_pk_add_f32 v[138:139], v[36:37], v[138:139]
	v_pk_add_f32 v[140:141], v[38:39], v[130:131]
	v_lshlrev_b32_e32 v130, 16, v132
	v_and_b32_e32 v131, 0xffff0000, v132
	v_lshlrev_b32_e32 v132, 16, v133
	v_and_b32_e32 v133, 0xffff0000, v133
	v_pk_add_f32 v[130:131], v[32:33], v[130:131]
	v_pk_add_f32 v[132:133], v[34:35], v[132:133]
	global_store_dwordx4 v[146:147], v[138:141], off offset:512
	global_store_dwordx4 v[146:147], v[130:133], off offset:528
	v_add_u32_e32 v182, 0x80, v176
	v_ashrrev_i32_e32 v183, 31, v182
	v_lshlrev_b64 v[130:131], 11, v[182:183]
	v_add_u32_e32 v190, 0x90, v176
	v_lshl_add_u64 v[130:131], v[136:137], 0, v[130:131]
	v_ashrrev_i32_e32 v191, 31, v190
	flat_load_dwordx4 v[138:141], v[130:131]
	flat_load_dwordx4 v[142:145], v[130:131] offset:256
	v_lshlrev_b64 v[130:131], 11, v[190:191]
	v_add_u32_e32 v192, 0xa0, v176
	v_lshl_add_u64 v[130:131], v[136:137], 0, v[130:131]
	v_ashrrev_i32_e32 v193, 31, v192
	flat_load_dwordx4 v[146:149], v[130:131]
	flat_load_dwordx4 v[150:153], v[130:131] offset:256
	v_lshlrev_b64 v[130:131], 11, v[192:193]
	v_add_u32_e32 v194, 0xb0, v176
	v_lshl_add_u64 v[130:131], v[136:137], 0, v[130:131]
	v_ashrrev_i32_e32 v195, 31, v194
	flat_load_dwordx4 v[154:157], v[130:131]
	flat_load_dwordx4 v[158:161], v[130:131] offset:256
	v_lshlrev_b64 v[130:131], 11, v[194:195]
	v_lshl_add_u64 v[130:131], v[136:137], 0, v[130:131]
	flat_load_dwordx4 v[178:181], v[130:131]
	s_nop 0
	flat_load_dwordx4 v[130:133], v[130:131] offset:256
	v_lshlrev_b64 v[136:137], 12, v[182:183]
	v_lshl_add_u64 v[196:197], v[134:135], 0, v[136:137]
	s_waitcnt vmcnt(0) lgkmcnt(0)
; __device__ __forceinline__ float lo16(unsigned v) { return __uint_as_float(v << 16); }
; __device__ __forceinline__ float hi16(unsigned v) { return __uint_as_float(v & 0xffff0000u); }
;   __device__ __forceinline__ void operator()(const f32x4 (&acc)[2][2][4][2], const pg8::Unit& u, int wr, int wc, int fr, int fq) const {
;     ...
; #pragma unroll
;         for (int m = 0; m < 4; ++m) {
;           const int row = row0 + ai * 128 + m * 16;
; #pragma unroll
;           for (int bj = 0; bj < 2; ++bj) {
;             float* d = xo + (size_t)row * DM + col0 + bj * 128;
;             const u32x4 x4 = xv[m][bj];
;             f32x4 o0 = acc[ai][bj][m][0], o1 = acc[ai][bj][m][1];
;             o0[0] += lo16(x4.x); o0[1] += hi16(x4.x); o0[2] += lo16(x4.y); o0[3] += hi16(x4.y); o1[0] += lo16(x4.z); o1[1] += hi16(x4.z); o1[2] += lo16(x4.w); o1[3] += hi16(x4.w);
;             *(f32x4*)d = o0; *(f32x4*)(d + 4) = o1;
;           }
;         }
	v_lshlrev_b32_e32 v136, 16, v138
	v_and_b32_e32 v137, 0xffff0000, v138
	v_lshlrev_b32_e32 v138, 16, v139
	v_and_b32_e32 v139, 0xffff0000, v139
	v_pk_add_f32 v[136:137], v[94:95], v[136:137]
	v_pk_add_f32 v[138:139], v[96:97], v[138:139]
	v_lshlrev_b32_e32 v182, 16, v140
	v_and_b32_e32 v183, 0xffff0000, v140
	v_lshlrev_b32_e32 v140, 16, v141
	v_and_b32_e32 v141, 0xffff0000, v141
	v_pk_add_f32 v[182:183], v[90:91], v[182:183]
	v_pk_add_f32 v[184:185], v[92:93], v[140:141]
	global_store_dwordx4 v[196:197], v[136:139], off
	global_store_dwordx4 v[196:197], v[182:185], off offset:16
	v_lshlrev_b32_e32 v140, 16, v144
	v_lshlrev_b32_e32 v136, 16, v142
	v_and_b32_e32 v137, 0xffff0000, v142
	v_lshlrev_b32_e32 v138, 16, v143
	v_and_b32_e32 v139, 0xffff0000, v143
	v_pk_add_f32 v[136:137], v[28:29], v[136:137]
	v_pk_add_f32 v[138:139], v[30:31], v[138:139]
	v_and_b32_e32 v141, 0xffff0000, v144
	v_lshlrev_b32_e32 v142, 16, v145
	v_and_b32_e32 v143, 0xffff0000, v145
	v_pk_add_f32 v[140:141], v[24:25], v[140:141]
	v_pk_add_f32 v[142:143], v[26:27], v[142:143]
	global_store_dwordx4 v[196:197], v[136:139], off offset:512
	global_store_dwordx4 v[196:197], v[140:143], off offset:528
	s_nop 0
	v_lshlrev_b64 v[136:137], 12, v[190:191]
	v_lshl_add_u64 v[144:145], v[134:135], 0, v[136:137]
	v_lshlrev_b32_e32 v136, 16, v146
	v_and_b32_e32 v137, 0xffff0000, v146
	v_lshlrev_b32_e32 v138, 16, v147
	v_and_b32_e32 v139, 0xffff0000, v147
	v_pk_add_f32 v[136:137], v[86:87], v[136:137]
	v_pk_add_f32 v[138:139], v[88:89], v[138:139]
	v_lshlrev_b32_e32 v140, 16, v148
	v_and_b32_e32 v141, 0xffff0000, v148
	v_lshlrev_b32_e32 v142, 16, v149
	v_and_b32_e32 v143, 0xffff0000, v149
	v_pk_add_f32 v[140:141], v[82:83], v[140:141]
	v_pk_add_f32 v[142:143], v[84:85], v[142:143]
	global_store_dwordx4 v[144:145], v[136:139], off
	global_store_dwordx4 v[144:145], v[140:143], off offset:16
	s_nop 0
	v_lshlrev_b32_e32 v136, 16, v150
	v_and_b32_e32 v137, 0xffff0000, v150
	v_lshlrev_b32_e32 v138, 16, v151
	v_and_b32_e32 v139, 0xffff0000, v151
	v_pk_add_f32 v[136:137], v[20:21], v[136:137]
	v_pk_add_f32 v[138:139], v[22:23], v[138:139]
	v_lshlrev_b32_e32 v140, 16, v152
	v_and_b32_e32 v141, 0xffff0000, v152
	v_lshlrev_b32_e32 v142, 16, v153
	v_and_b32_e32 v143, 0xffff0000, v153
	v_pk_add_f32 v[140:141], v[16:17], v[140:141]
	v_pk_add_f32 v[142:143], v[18:19], v[142:143]
	global_store_dwordx4 v[144:145], v[136:139], off offset:512
	global_store_dwordx4 v[144:145], v[140:143], off offset:528
	s_nop 0
	v_lshlrev_b64 v[136:137], 12, v[192:193]
	v_lshl_add_u64 v[144:145], v[134:135], 0, v[136:137]
	v_lshlrev_b32_e32 v136, 16, v154
	v_and_b32_e32 v137, 0xffff0000, v154
	v_lshlrev_b32_e32 v138, 16, v155
	v_and_b32_e32 v139, 0xffff0000, v155
	v_pk_add_f32 v[136:137], v[76:77], v[136:137]
	v_pk_add_f32 v[138:139], v[78:79], v[138:139]
	v_lshlrev_b32_e32 v140, 16, v156
	v_and_b32_e32 v141, 0xffff0000, v156
	v_lshlrev_b32_e32 v142, 16, v157
	v_and_b32_e32 v143, 0xffff0000, v157
	v_pk_add_f32 v[140:141], v[72:73], v[140:141]
	v_pk_add_f32 v[142:143], v[74:75], v[142:143]
	global_store_dwordx4 v[144:145], v[136:139], off
	global_store_dwordx4 v[144:145], v[140:143], off offset:16
	s_nop 0
	v_lshlrev_b32_e32 v136, 16, v158
	v_and_b32_e32 v137, 0xffff0000, v158
	v_lshlrev_b32_e32 v138, 16, v159
	v_and_b32_e32 v139, 0xffff0000, v159
	v_pk_add_f32 v[136:137], v[12:13], v[136:137]
	v_pk_add_f32 v[138:139], v[14:15], v[138:139]
	v_lshlrev_b32_e32 v140, 16, v160
	v_and_b32_e32 v141, 0xffff0000, v160
	v_lshlrev_b32_e32 v142, 16, v161
	v_and_b32_e32 v143, 0xffff0000, v161
	v_pk_add_f32 v[140:141], v[8:9], v[140:141]
	v_pk_add_f32 v[142:143], v[10:11], v[142:143]
	global_store_dwordx4 v[144:145], v[136:139], off offset:512
	global_store_dwordx4 v[144:145], v[140:143], off offset:528
	s_nop 0
	v_lshlrev_b64 v[136:137], 12, v[194:195]
	v_lshl_add_u64 v[142:143], v[134:135], 0, v[136:137]
	v_lshlrev_b32_e32 v134, 16, v178
	v_and_b32_e32 v135, 0xffff0000, v178
	v_lshlrev_b32_e32 v136, 16, v179
	v_and_b32_e32 v137, 0xffff0000, v179
	v_pk_add_f32 v[134:135], v[68:69], v[134:135]
	v_pk_add_f32 v[136:137], v[70:71], v[136:137]
	v_lshlrev_b32_e32 v138, 16, v180
	v_and_b32_e32 v139, 0xffff0000, v180
	v_lshlrev_b32_e32 v140, 16, v181
	v_and_b32_e32 v141, 0xffff0000, v181
	v_pk_add_f32 v[138:139], v[64:65], v[138:139]
	v_pk_add_f32 v[140:141], v[66:67], v[140:141]
	global_store_dwordx4 v[142:143], v[134:137], off
	global_store_dwordx4 v[142:143], v[138:141], off offset:16
	s_nop 0
	v_lshlrev_b32_e32 v134, 16, v130
	v_and_b32_e32 v135, 0xffff0000, v130
	v_lshlrev_b32_e32 v130, 16, v131
	v_and_b32_e32 v131, 0xffff0000, v131
	v_pk_add_f32 v[134:135], v[4:5], v[134:135]
	v_pk_add_f32 v[136:137], v[6:7], v[130:131]
	v_lshlrev_b32_e32 v130, 16, v132
	v_and_b32_e32 v131, 0xffff0000, v132
	v_lshlrev_b32_e32 v132, 16, v133
	v_and_b32_e32 v133, 0xffff0000, v133
	v_pk_add_f32 v[130:131], v[0:1], v[130:131]
	v_pk_add_f32 v[132:133], v[2:3], v[132:133]
	global_store_dwordx4 v[142:143], v[134:137], off offset:512
	global_store_dwordx4 v[142:143], v[130:133], off offset:528
	s_mov_b64 s[10:11], 0
